# stack + mixer: independent halo loads issued together (serial load/wait chains that only shared registers removed), one vmcnt(0) relaxed to vmcnt(3)
# baseline (speedup 1.0000x reference)
; __device__ __forceinline__ f32x2 ld2(const bf16_t* p) { const unsigned u = *(const unsigned*)p; return (f32x2){bf_lo(u), bf_hi(u)}; }
; __device__ __forceinline__ f32x2 un2(unsigned u) { return (f32x2){bf_lo(u), bf_hi(u)}; }
; __device__ __forceinline__ void st2(bf16_t* p, f32x2 v) { *(unsigned*)p = cvt_pk_bf16(v.x, v.y); }
; #define MIX_ISSUED() asm volatile("" ::: "memory")
; __device__ __forceinline__ void mixer_phase(const Args& a, int l, LAS unsigned char* lds, int tile0, int tstride, int tend) {
;     ...
;         const int t0 = ti * TT, s0 = t0 % SEQ; const bool first = (s0 == 0);
;         const bf16_t* Pt = P + (size_t)t0 * NCO + e0;
;         {
;             const float* cw = a.in[I_CAW] + (size_t)l * 3 * EW + e0;
;             const f32x2 w0 = *(const f32x2*)cw, w1 = *(const f32x2*)(cw + EW), w2 = *(const f32x2*)(cw + 2 * EW);
;             f32x2 q2 = (f32x2){0.f, 0.f}, q1 = (f32x2){0.f, 0.f};
;             if (!first) { q2 = ld2(Pt - 2 * (ptrdiff_t)NCO + OQ); q1 = ld2(Pt - (ptrdiff_t)NCO + OQ); }
;             unsigned rA[TT][2];
; #pragma unroll
;             for (int i = 0; i < TT; ++i) { const bf16_t* pr = Pt + (size_t)i * NCO; rA[i][0] = *(const unsigned*)(pr + OQ); rA[i][1] = *(const unsigned*)(pr + OAB); }
;             MIX_ISSUED();
; #pragma unroll
;             for (int i = 0; i < TT; ++i) {
;                 const f32x2 q = un2(rA[i][0]), abz = un2(rA[i][1]);
;                 const f32x2 cv = w0 * q2 + w1 * q1 + w2 * q;
;                 st2(Y + (size_t)(t0 + i) * YW + e0, abz * cv);
;                 q2 = q1; q1 = q;
;             }
;         }
.LBB0_378:
	global_load_dwordx2 v[4:5], v[14:15], off
	global_load_dwordx2 v[104:105], v[32:33], off
	global_load_dwordx2 v[6:7], v[34:35], off
	s_add_i32 s92, s9, -15
	s_ashr_i32 s93, s92, 31
	s_lshr_b32 s4, s93, 21
	s_add_i32 s4, s92, s4
	s_and_b32 s4, s4, 0xfffff800
	s_sub_i32 s23, s92, s4
	s_cmp_eq_u32 s23, 0
	s_cselect_b64 s[54:55], -1, 0
	s_cmp_lg_u32 s23, 0
	s_cselect_b64 s[94:95], -1, 0
	v_mad_i64_i32 v[2:3], s[4:5], s92, v192, v[26:27]
	v_mov_b32_e32 v106, 0
	s_and_b64 vcc, exec, s[54:55]
	v_mov_b32_e32 v107, 0
	v_mov_b32_e32 v108, 0
	v_mov_b32_e32 v109, 0
	s_cbranch_vccnz .LBB0_380
	v_add_co_u32_e32 v8, vcc, 0xffff7000, v2
	s_nop 1
	v_addc_co_u32_e32 v9, vcc, -1, v3, vcc
	global_load_dword v10, v[8:9], off
	v_add_co_u32_e32 v8, vcc, 0xffffc000, v2
	s_nop 1
	v_addc_co_u32_e32 v9, vcc, -1, v3, vcc
	global_load_dword v8, v[8:9], off offset:-2048
	s_waitcnt vmcnt(0)
	v_lshlrev_b32_e32 v108, 16, v10
	v_and_b32_e32 v109, 0xffff0000, v10
	v_lshlrev_b32_e32 v106, 16, v8
	v_and_b32_e32 v107, 0xffff0000, v8
.LBB0_380:
	global_load_dword v111, v[2:3], off
	global_load_dword v113, v[2:3], off offset:2048
	v_add_co_u32_e32 v8, vcc, 0x4000, v2
	s_mov_b32 s4, 0xe000
	s_nop 0
	v_addc_co_u32_e32 v9, vcc, 0, v3, vcc
	global_load_dword v116, v[8:9], off offset:2048
	v_add_co_u32_e32 v8, vcc, 0x5000, v2
	s_waitcnt vmcnt(3)
	v_pk_mul_f32 v[108:109], v[4:5], v[108:109]
	v_addc_co_u32_e32 v9, vcc, 0, v3, vcc
	global_load_dword v117, v[8:9], off
	v_add_co_u32_e32 v8, vcc, 0x9000, v2
	s_waitcnt vmcnt(5)
	v_pk_fma_f32 v[108:109], v[104:105], v[106:107], v[108:109]
	v_addc_co_u32_e32 v9, vcc, 0, v3, vcc
	global_load_dword v118, v[8:9], off
	global_load_dword v119, v[8:9], off offset:2048
	v_add_co_u32_e32 v8, vcc, 0xd000, v2
	s_add_i32 s11, s9, -14
	s_nop 0
	v_addc_co_u32_e32 v9, vcc, 0, v3, vcc
	global_load_dword v120, v[8:9], off offset:2048
	v_add_co_u32_e32 v8, vcc, s4, v2
	s_mov_b32 s4, 0x12000
	s_nop 0
	v_addc_co_u32_e32 v9, vcc, 0, v3, vcc
	global_load_dword v121, v[8:9], off
	v_add_co_u32_e32 v10, vcc, s4, v2
	s_mov_b32 s4, 0x16000
	s_nop 0
	v_addc_co_u32_e32 v11, vcc, 0, v3, vcc
	global_load_dword v122, v[10:11], off
	global_load_dword v123, v[10:11], off offset:2048
	v_add_co_u32_e32 v10, vcc, s4, v2
	s_mov_b32 s4, 0x17000
	s_nop 0
	v_addc_co_u32_e32 v11, vcc, 0, v3, vcc
	v_add_co_u32_e32 v12, vcc, s4, v2
	global_load_dword v124, v[10:11], off offset:2048
	s_nop 0
	v_addc_co_u32_e32 v13, vcc, 0, v3, vcc
	global_load_dword v125, v[12:13], off
	s_mov_b32 s4, 0x1b000
	v_add_co_u32_e32 v10, vcc, s4, v2
	s_mov_b32 s4, 0x1f000
	s_nop 0
	v_addc_co_u32_e32 v11, vcc, 0, v3, vcc
	global_load_dword v126, v[10:11], off
	global_load_dword v127, v[10:11], off offset:2048
	v_add_co_u32_e32 v10, vcc, s4, v2
	s_mov_b32 s4, 0x20000
	s_nop 0
	v_addc_co_u32_e32 v11, vcc, 0, v3, vcc
	global_load_dword v128, v[10:11], off offset:2048
	v_add_co_u32_e32 v10, vcc, s4, v2
	s_mov_b32 s4, 0x24000
	s_nop 0
	v_addc_co_u32_e32 v11, vcc, 0, v3, vcc
	global_load_dword v129, v[10:11], off
	v_add_co_u32_e32 v96, vcc, s4, v2
	s_mov_b32 s4, 0x28000
	s_nop 0
	v_addc_co_u32_e32 v97, vcc, 0, v3, vcc
	global_load_dword v130, v[96:97], off
	global_load_dword v131, v[96:97], off offset:2048
	v_add_co_u32_e32 v96, vcc, s4, v2
	s_mov_b32 s4, 0x29000
	s_nop 0
	v_addc_co_u32_e32 v97, vcc, 0, v3, vcc
	global_load_dword v132, v[96:97], off offset:2048
	v_add_co_u32_e32 v96, vcc, s4, v2
	s_mov_b32 s4, 0x2d000
	s_nop 0
	v_addc_co_u32_e32 v97, vcc, 0, v3, vcc
	global_load_dword v133, v[96:97], off
	v_add_co_u32_e32 v98, vcc, s4, v2
	s_mov_b32 s4, 0x31000
	s_nop 0
	v_addc_co_u32_e32 v99, vcc, 0, v3, vcc
	global_load_dword v134, v[98:99], off
	global_load_dword v135, v[98:99], off offset:2048
	v_add_co_u32_e32 v98, vcc, s4, v2
	s_mov_b32 s4, 0x32000
	s_nop 0
	v_addc_co_u32_e32 v99, vcc, 0, v3, vcc
	global_load_dword v136, v[98:99], off offset:2048
	v_add_co_u32_e32 v98, vcc, s4, v2
	s_mov_b32 s4, 0x36000
	s_nop 0
	v_addc_co_u32_e32 v99, vcc, 0, v3, vcc
	global_load_dword v137, v[98:99], off
	v_add_co_u32_e32 v100, vcc, s4, v2
	s_mov_b32 s4, 0x3a000
	s_nop 0
	v_addc_co_u32_e32 v101, vcc, 0, v3, vcc
	global_load_dword v138, v[100:101], off
	global_load_dword v139, v[100:101], off offset:2048
	v_add_co_u32_e32 v100, vcc, s4, v2
	s_mov_b32 s4, 0x3b000
	s_nop 0
	v_addc_co_u32_e32 v101, vcc, 0, v3, vcc
	global_load_dword v140, v[100:101], off offset:2048
	v_add_co_u32_e32 v100, vcc, s4, v2
	s_mov_b32 s4, 0x3f000
	s_nop 0
	v_addc_co_u32_e32 v101, vcc, 0, v3, vcc
	global_load_dword v141, v[100:101], off
	v_add_co_u32_e32 v102, vcc, s4, v2
	s_mov_b32 s4, 0x43000
	s_nop 0
	v_addc_co_u32_e32 v103, vcc, 0, v3, vcc
	global_load_dword v142, v[102:103], off
	global_load_dword v143, v[102:103], off offset:2048
	v_add_co_u32_e32 v102, vcc, s4, v2
	s_mov_b32 s4, 0x44000
	s_nop 0
	v_addc_co_u32_e32 v103, vcc, 0, v3, vcc
	global_load_dword v144, v[102:103], off offset:2048
	v_add_co_u32_e32 v102, vcc, s4, v2
	s_waitcnt vmcnt(30)
	v_lshlrev_b32_e32 v110, 16, v111
	v_addc_co_u32_e32 v103, vcc, 0, v3, vcc
	global_load_dword v145, v[102:103], off
	v_and_b32_e32 v111, 0xffff0000, v111
	s_waitcnt vmcnt(30)
	v_lshlrev_b32_e32 v112, 16, v113
	v_and_b32_e32 v113, 0xffff0000, v113
	v_pk_fma_f32 v[108:109], v[6:7], v[110:111], v[108:109]
	v_mad_i64_i32 v[114:115], s[4:5], s92, v193, v[28:29]
	v_pk_mul_f32 v[108:109], v[108:109], v[112:113]
	s_waitcnt vmcnt(28)
	v_lshlrev_b32_e32 v112, 16, v117
	v_cvt_pk_bf16_f32 v108, v108, v109
	global_store_dword v[114:115], v108, off
	v_pk_mul_f32 v[114:115], v[104:105], v[110:111]
	v_lshlrev_b32_e32 v108, 16, v116
	v_and_b32_e32 v109, 0xffff0000, v116
	v_pk_fma_f32 v[106:107], v[4:5], v[106:107], v[114:115]
	v_and_b32_e32 v113, 0xffff0000, v117
	v_pk_fma_f32 v[106:107], v[6:7], v[108:109], v[106:107]
	v_mad_i64_i32 v[114:115], s[4:5], s11, v193, v[28:29]
	v_pk_mul_f32 v[106:107], v[106:107], v[112:113]
	s_waitcnt vmcnt(27)
; __device__ __forceinline__ f32x2 un2(unsigned u) { return (f32x2){bf_lo(u), bf_hi(u)}; }
; __device__ __forceinline__ void st2(bf16_t* p, f32x2 v) { *(unsigned*)p = cvt_pk_bf16(v.x, v.y); }
; __device__ __forceinline__ void mixer_phase(const Args& a, int l, LAS unsigned char* lds, int tile0, int tstride, int tend) {
;     ...
; #pragma unroll
;             for (int i = 0; i < TT; ++i) {
;                 const f32x2 q = un2(rA[i][0]), abz = un2(rA[i][1]);
;                 const f32x2 cv = w0 * q2 + w1 * q1 + w2 * q;
;                 st2(Y + (size_t)(t0 + i) * YW + e0, abz * cv);
;                 q2 = q1; q1 = q;
;             }
	v_lshlrev_b32_e32 v112, 16, v119
	v_cvt_pk_bf16_f32 v106, v106, v107
	global_store_dword v[114:115], v106, off
	v_pk_mul_f32 v[114:115], v[104:105], v[108:109]
	v_lshlrev_b32_e32 v106, 16, v118
	v_and_b32_e32 v107, 0xffff0000, v118
	v_pk_fma_f32 v[110:111], v[4:5], v[110:111], v[114:115]
	v_and_b32_e32 v113, 0xffff0000, v119
	v_pk_fma_f32 v[110:111], v[6:7], v[106:107], v[110:111]
	s_add_i32 s15, s9, -13
	v_pk_mul_f32 v[110:111], v[110:111], v[112:113]
	v_mad_i64_i32 v[114:115], s[4:5], s15, v193, v[28:29]
	v_cvt_pk_bf16_f32 v110, v110, v111
	global_store_dword v[114:115], v110, off
	v_pk_mul_f32 v[114:115], v[104:105], v[106:107]
	s_waitcnt vmcnt(28)
	v_lshlrev_b32_e32 v110, 16, v120
	v_and_b32_e32 v111, 0xffff0000, v120
	v_pk_fma_f32 v[108:109], v[4:5], v[108:109], v[114:115]
	s_waitcnt vmcnt(27)
	v_lshlrev_b32_e32 v112, 16, v121
	v_and_b32_e32 v113, 0xffff0000, v121
	v_pk_fma_f32 v[108:109], v[6:7], v[110:111], v[108:109]
	s_add_i32 s16, s9, -12
	v_pk_mul_f32 v[108:109], v[108:109], v[112:113]
	v_mad_i64_i32 v[114:115], s[4:5], s16, v193, v[28:29]
	v_cvt_pk_bf16_f32 v108, v108, v109
	global_store_dword v[114:115], v108, off
	v_pk_mul_f32 v[114:115], v[104:105], v[110:111]
	s_waitcnt vmcnt(27)
	v_lshlrev_b32_e32 v108, 16, v122
	v_and_b32_e32 v109, 0xffff0000, v122
	v_pk_fma_f32 v[106:107], v[4:5], v[106:107], v[114:115]
	s_waitcnt vmcnt(26)
	v_lshlrev_b32_e32 v112, 16, v123
	v_and_b32_e32 v113, 0xffff0000, v123
	v_pk_fma_f32 v[106:107], v[6:7], v[108:109], v[106:107]
	s_add_i32 s17, s9, -11
	v_pk_mul_f32 v[106:107], v[106:107], v[112:113]
	v_mad_i64_i32 v[114:115], s[4:5], s17, v193, v[28:29]
	v_cvt_pk_bf16_f32 v106, v106, v107
	global_store_dword v[114:115], v106, off
	v_pk_mul_f32 v[114:115], v[104:105], v[108:109]
	s_waitcnt vmcnt(26)
	v_lshlrev_b32_e32 v106, 16, v124
	v_and_b32_e32 v107, 0xffff0000, v124
	v_pk_fma_f32 v[110:111], v[4:5], v[110:111], v[114:115]
	s_waitcnt vmcnt(25)
	v_lshlrev_b32_e32 v112, 16, v125
	v_and_b32_e32 v113, 0xffff0000, v125
	v_pk_fma_f32 v[110:111], v[6:7], v[106:107], v[110:111]
	s_add_i32 s80, s9, -10
	v_pk_mul_f32 v[110:111], v[110:111], v[112:113]
	v_mad_i64_i32 v[114:115], s[4:5], s80, v193, v[28:29]
	v_cvt_pk_bf16_f32 v110, v110, v111
	global_store_dword v[114:115], v110, off
	v_pk_mul_f32 v[114:115], v[104:105], v[106:107]
	s_waitcnt vmcnt(25)
	v_lshlrev_b32_e32 v110, 16, v126
	v_and_b32_e32 v111, 0xffff0000, v126
	v_pk_fma_f32 v[108:109], v[4:5], v[108:109], v[114:115]
	s_waitcnt vmcnt(24)
	v_lshlrev_b32_e32 v112, 16, v127
	v_and_b32_e32 v113, 0xffff0000, v127
	v_pk_fma_f32 v[108:109], v[6:7], v[110:111], v[108:109]
	s_add_i32 s81, s9, -9
	v_pk_mul_f32 v[108:109], v[108:109], v[112:113]
	v_mad_i64_i32 v[114:115], s[4:5], s81, v193, v[28:29]
	v_cvt_pk_bf16_f32 v108, v108, v109
	global_store_dword v[114:115], v108, off
	v_pk_mul_f32 v[114:115], v[104:105], v[110:111]
	s_waitcnt vmcnt(24)
	v_lshlrev_b32_e32 v108, 16, v128
	v_and_b32_e32 v109, 0xffff0000, v128
	v_pk_fma_f32 v[106:107], v[4:5], v[106:107], v[114:115]
	s_waitcnt vmcnt(23)
	v_lshlrev_b32_e32 v112, 16, v129
	v_and_b32_e32 v113, 0xffff0000, v129
	v_pk_fma_f32 v[106:107], v[6:7], v[108:109], v[106:107]
	s_add_i32 s82, s9, -8
	v_pk_mul_f32 v[106:107], v[106:107], v[112:113]
	v_mad_i64_i32 v[114:115], s[4:5], s82, v193, v[28:29]
	v_cvt_pk_bf16_f32 v106, v106, v107
	global_store_dword v[114:115], v106, off
	v_pk_mul_f32 v[114:115], v[104:105], v[108:109]
	s_waitcnt vmcnt(23)
	v_lshlrev_b32_e32 v106, 16, v130
	v_and_b32_e32 v107, 0xffff0000, v130
	v_pk_fma_f32 v[110:111], v[4:5], v[110:111], v[114:115]
	s_waitcnt vmcnt(22)
	v_lshlrev_b32_e32 v112, 16, v131
	v_and_b32_e32 v113, 0xffff0000, v131
	v_pk_fma_f32 v[110:111], v[6:7], v[106:107], v[110:111]
	s_add_i32 s83, s9, -7
	v_pk_mul_f32 v[110:111], v[110:111], v[112:113]
	v_mad_i64_i32 v[114:115], s[4:5], s83, v193, v[28:29]
	v_cvt_pk_bf16_f32 v110, v110, v111
	global_store_dword v[114:115], v110, off
	v_pk_mul_f32 v[114:115], v[104:105], v[106:107]
	s_waitcnt vmcnt(22)
; __device__ __forceinline__ f32x2 un2(unsigned u) { return (f32x2){bf_lo(u), bf_hi(u)}; }
; __device__ __forceinline__ void st2(bf16_t* p, f32x2 v) { *(unsigned*)p = cvt_pk_bf16(v.x, v.y); }
; __device__ __forceinline__ void mixer_phase(const Args& a, int l, LAS unsigned char* lds, int tile0, int tstride, int tend) {
;     ...
;             for (int i = 0; i < TT; ++i) {
;                 const f32x2 q = un2(rA[i][0]), abz = un2(rA[i][1]);
;                 const f32x2 cv = w0 * q2 + w1 * q1 + w2 * q;
;                 st2(Y + (size_t)(t0 + i) * YW + e0, abz * cv);
;                 q2 = q1; q1 = q;
;             }
;         }
;         asm volatile("" ::: "memory");
;         {
;             const bf16_t* Pb = Pt + OBIN; bf16_t* po = PO + (size_t)t0 * EW + e0;
;             const int grp = wave >> 1;
;             if (grp == 0) pool_branch<2>(Pb, po, first);
;             else if (grp == 1) pool_branch<4>(Pb, po, first);
;             else if (grp == 2) pool_branch<8>(Pb, po, first);
;             else pool_branch<16>(Pb, po, first);
	v_lshlrev_b32_e32 v110, 16, v132
	v_and_b32_e32 v111, 0xffff0000, v132
	v_pk_fma_f32 v[108:109], v[4:5], v[108:109], v[114:115]
	s_waitcnt vmcnt(21)
	v_lshlrev_b32_e32 v112, 16, v133
	v_and_b32_e32 v113, 0xffff0000, v133
	v_pk_fma_f32 v[108:109], v[6:7], v[110:111], v[108:109]
	s_add_i32 s89, s9, -6
	v_pk_mul_f32 v[108:109], v[108:109], v[112:113]
	v_mad_i64_i32 v[114:115], s[4:5], s89, v193, v[28:29]
	v_cvt_pk_bf16_f32 v108, v108, v109
	global_store_dword v[114:115], v108, off
	v_pk_mul_f32 v[114:115], v[104:105], v[110:111]
	s_waitcnt vmcnt(21)
	v_lshlrev_b32_e32 v108, 16, v134
	v_and_b32_e32 v109, 0xffff0000, v134
	v_pk_fma_f32 v[106:107], v[4:5], v[106:107], v[114:115]
	s_waitcnt vmcnt(20)
	v_lshlrev_b32_e32 v112, 16, v135
	v_and_b32_e32 v113, 0xffff0000, v135
	v_pk_fma_f32 v[106:107], v[6:7], v[108:109], v[106:107]
	s_add_i32 s18, s9, -5
	v_pk_mul_f32 v[106:107], v[106:107], v[112:113]
	v_mad_i64_i32 v[114:115], s[4:5], s18, v193, v[28:29]
	v_cvt_pk_bf16_f32 v106, v106, v107
	global_store_dword v[114:115], v106, off
	v_pk_mul_f32 v[114:115], v[104:105], v[108:109]
	s_waitcnt vmcnt(20)
	v_lshlrev_b32_e32 v106, 16, v136
	v_and_b32_e32 v107, 0xffff0000, v136
	v_pk_fma_f32 v[110:111], v[4:5], v[110:111], v[114:115]
	s_waitcnt vmcnt(19)
	v_lshlrev_b32_e32 v112, 16, v137
	v_and_b32_e32 v113, 0xffff0000, v137
	v_pk_fma_f32 v[110:111], v[6:7], v[106:107], v[110:111]
	s_add_i32 s19, s9, -4
	v_pk_mul_f32 v[110:111], v[110:111], v[112:113]
	v_mad_i64_i32 v[114:115], s[4:5], s19, v193, v[28:29]
	v_cvt_pk_bf16_f32 v110, v110, v111
	global_store_dword v[114:115], v110, off
	v_pk_mul_f32 v[114:115], v[104:105], v[106:107]
	s_waitcnt vmcnt(19)
	v_lshlrev_b32_e32 v110, 16, v138
	v_and_b32_e32 v111, 0xffff0000, v138
	v_pk_fma_f32 v[108:109], v[4:5], v[108:109], v[114:115]
	s_waitcnt vmcnt(18)
	v_lshlrev_b32_e32 v112, 16, v139
	v_and_b32_e32 v113, 0xffff0000, v139
	v_pk_fma_f32 v[108:109], v[6:7], v[110:111], v[108:109]
	s_add_i32 s20, s9, -3
	v_pk_mul_f32 v[108:109], v[108:109], v[112:113]
	v_mad_i64_i32 v[114:115], s[4:5], s20, v193, v[28:29]
	v_cvt_pk_bf16_f32 v108, v108, v109
	global_store_dword v[114:115], v108, off
	v_pk_mul_f32 v[114:115], v[104:105], v[110:111]
	s_waitcnt vmcnt(18)
	v_lshlrev_b32_e32 v108, 16, v140
	v_and_b32_e32 v109, 0xffff0000, v140
	v_pk_fma_f32 v[106:107], v[4:5], v[106:107], v[114:115]
	s_waitcnt vmcnt(17)
	v_lshlrev_b32_e32 v112, 16, v141
	v_and_b32_e32 v113, 0xffff0000, v141
	v_pk_fma_f32 v[106:107], v[6:7], v[108:109], v[106:107]
	s_add_i32 s21, s9, -2
	v_pk_mul_f32 v[106:107], v[106:107], v[112:113]
	v_mad_i64_i32 v[114:115], s[4:5], s21, v193, v[28:29]
	v_cvt_pk_bf16_f32 v106, v106, v107
	global_store_dword v[114:115], v106, off
	v_pk_mul_f32 v[114:115], v[104:105], v[108:109]
	s_waitcnt vmcnt(17)
	v_lshlrev_b32_e32 v106, 16, v142
	v_and_b32_e32 v107, 0xffff0000, v142
	v_pk_fma_f32 v[110:111], v[4:5], v[110:111], v[114:115]
	s_waitcnt vmcnt(16)
	v_lshlrev_b32_e32 v112, 16, v143
	v_and_b32_e32 v113, 0xffff0000, v143
	v_pk_fma_f32 v[110:111], v[6:7], v[106:107], v[110:111]
	s_add_i32 s22, s9, -1
	v_pk_mul_f32 v[110:111], v[110:111], v[112:113]
	v_mad_i64_i32 v[114:115], s[4:5], s22, v193, v[28:29]
	v_cvt_pk_bf16_f32 v110, v110, v111
	v_pk_mul_f32 v[104:105], v[104:105], v[106:107]
	global_store_dword v[114:115], v110, off
	s_waitcnt vmcnt(16)
	v_lshlrev_b32_e32 v110, 16, v144
	v_and_b32_e32 v111, 0xffff0000, v144
	v_pk_fma_f32 v[4:5], v[4:5], v[108:109], v[104:105]
	s_waitcnt vmcnt(15)
	v_lshlrev_b32_e32 v112, 16, v145
	v_and_b32_e32 v113, 0xffff0000, v145
	v_pk_fma_f32 v[4:5], v[6:7], v[110:111], v[4:5]
	v_mad_i64_i32 v[6:7], s[4:5], s9, v193, v[28:29]
	v_pk_mul_f32 v[4:5], v[4:5], v[112:113]
	s_lshl_b64 s[4:5], s[92:93], 11
	v_cvt_pk_bf16_f32 v4, v4, v5
	global_store_dword v[6:7], v4, off
	v_lshl_add_u64 v[6:7], v[2:3], 0, s[78:79]
	v_lshl_add_u64 v[4:5], v[30:31], 0, s[4:5]
	s_mov_b64 s[4:5], -1
	s_and_b64 vcc, exec, s[74:75]
	s_cbranch_vccz .LBB0_387
	s_mov_b64 s[6:7], -1
	s_mov_b64 s[62:63], 0
	s_cmp_lt_i32 s8, 2
	s_mov_b64 s[4:5], 0
	s_cbranch_scc0 .LBB0_401
	s_and_b64 vcc, exec, s[6:7]
	s_cbranch_vccnz .LBB0_404

; __device__ __forceinline__ f32x2 un2(unsigned u) { return (f32x2){bf_lo(u), bf_hi(u)}; }
; __device__ __forceinline__ void st2(bf16_t* p, f32x2 v) { *(unsigned*)p = cvt_pk_bf16(v.x, v.y); }
; template <int W>
; __device__ __forceinline__ void pool_branch(const bf16_t* __restrict__ Pb, bf16_t* __restrict__ out, bool first) {
;     unsigned raw[W - 1 + TT];
; #pragma unroll
;     for (int j = 0; j < W - 1 + TT; ++j) { const int off = j - (W - 1); const int offc = (off < 0 && first) ? 0 : off;
;         unsigned r = *(const unsigned*)(Pb + (ptrdiff_t)offc * NCO); if (off < 0 && first) r = 0u; raw[j] = r; }
;     asm volatile("" ::: "memory");
;     f32x2 S = (f32x2){0.f, 0.f};
; #pragma unroll
;     for (int j = 0; j < W - 1; ++j) S += un2(raw[j]);
; #pragma unroll
;     for (int i = 0; i < TT; ++i) {
;         const f32x2 ui = un2(raw[i + W - 1]);
;         S += ui;
;         const float inv = (first && (i + 1 < W)) ? 1.0f / (float)(i + 1) : 1.0f / (float)W;
;         st2(out + (size_t)i * EW, S * inv - ui);
;         S -= un2(raw[i]);
.LBB0_385:
	s_and_b64 s[4:5], exec, s[54:55]
	s_cselect_b32 s5, 0, -1
	s_cselect_b32 s4, 0, 0xffff2800
	v_lshl_add_u64 v[228:229], v[6:7], 0, s[4:5]
	global_load_dword v104, v[228:229], off
	s_cselect_b32 s4, 0, 0xffffb800
	global_load_dword v110, v[6:7], off
	s_mov_b32 s56, 0x3e800000
	v_lshl_add_u64 v[228:229], s[4:5], 1, v[6:7]
	global_load_dword v230, v[228:229], off
	v_lshl_add_u64 v[228:229], v[6:7], 0, s[4:5]
	global_load_dword v231, v[228:229], off
	s_movk_i32 s5, 0x5000
	s_mov_b32 s4, 0xa000
	s_waitcnt vmcnt(0)
	v_cndmask_b32_e64 v107, v104, 0, s[54:55]
	v_cndmask_b32_e64 v108, v230, 0, s[54:55]
	v_cndmask_b32_e64 v109, v231, 0, s[54:55]
	v_add_co_u32_e32 v104, vcc, s5, v2
	s_nop 1
	v_addc_co_u32_e32 v105, vcc, 0, v3, vcc
	global_load_dword v111, v[104:105], off offset:2048
	v_add_co_u32_e32 v104, vcc, s4, v2
	s_mov_b32 s4, 0x13000
	s_nop 0
	v_addc_co_u32_e32 v105, vcc, 0, v3, vcc
	global_load_dword v112, v[104:105], off
	global_load_dword v113, v[8:9], off offset:2048
	v_add_co_u32_e32 v8, vcc, s4, v2
	s_mov_b32 s4, 0x1c000
	s_nop 0
	v_addc_co_u32_e32 v9, vcc, 0, v3, vcc
	global_load_dword v105, v[8:9], off
	global_load_dword v104, v[12:13], off offset:2048
	v_add_co_u32_e32 v8, vcc, s4, v2
	s_mov_b32 s4, 0x25000
	s_nop 0
	v_addc_co_u32_e32 v9, vcc, 0, v3, vcc
	global_load_dword v114, v[8:9], off
	global_load_dword v115, v[10:11], off offset:2048
	v_add_co_u32_e32 v8, vcc, s4, v2
	s_mov_b32 s4, 0x2e000
	s_nop 0
	v_addc_co_u32_e32 v9, vcc, 0, v3, vcc
	global_load_dword v116, v[8:9], off
	global_load_dword v117, v[96:97], off offset:2048
	v_add_co_u32_e32 v8, vcc, s4, v2
	s_mov_b32 s4, 0x37000
	s_nop 0
	v_addc_co_u32_e32 v9, vcc, 0, v3, vcc
	global_load_dword v118, v[8:9], off
	global_load_dword v119, v[98:99], off offset:2048
	v_add_co_u32_e32 v8, vcc, s4, v2
	s_mov_b32 s4, 0x40000
	s_nop 0
	v_addc_co_u32_e32 v9, vcc, 0, v3, vcc
	global_load_dword v120, v[8:9], off
	global_load_dword v121, v[100:101], off offset:2048
	v_add_co_u32_e32 v8, vcc, s4, v2
	v_lshlrev_b32_e32 v96, 16, v107
	s_nop 0
	v_addc_co_u32_e32 v9, vcc, 0, v3, vcc
	global_load_dword v122, v[8:9], off
	global_load_dword v106, v[102:103], off offset:2048
	v_and_b32_e32 v97, 0xffff0000, v107
	v_pk_add_f32 v[8:9], v[96:97], 0 op_sel_hi:[1,0]
	v_lshlrev_b32_e32 v12, 16, v108
	v_and_b32_e32 v13, 0xffff0000, v108
	v_pk_add_f32 v[8:9], v[8:9], v[12:13]
	v_lshlrev_b32_e32 v10, 16, v109
	v_and_b32_e32 v11, 0xffff0000, v109
	v_pk_add_f32 v[98:99], v[8:9], v[10:11]
	v_lshlrev_b32_e32 v8, 16, v110
	v_and_b32_e32 v9, 0xffff0000, v110
	v_pk_add_f32 v[98:99], v[98:99], v[8:9]
	v_cndmask_b32_e64 v100, v196, 1.0, s[54:55]
	v_pk_fma_f32 v[100:101], v[100:101], v[98:99], v[8:9] op_sel_hi:[0,1,1] neg_lo:[0,0,1] neg_hi:[0,0,1]
	v_cvt_pk_bf16_f32 v100, v100, v101
	v_pk_add_f32 v[98:99], v[98:99], v[96:97] neg_lo:[0,1] neg_hi:[0,1]
	global_store_dword v[4:5], v100, off
	v_cndmask_b32_e64 v100, v196, 0.5, s[54:55]
	s_movk_i32 s4, 0x2000
	s_waitcnt vmcnt(15)
	v_lshlrev_b32_e32 v96, 16, v111
	v_and_b32_e32 v97, 0xffff0000, v111
	v_pk_add_f32 v[98:99], v[98:99], v[96:97]
	s_waitcnt vmcnt(13)
	v_lshlrev_b32_e32 v108, 16, v113
	v_pk_fma_f32 v[100:101], v[100:101], v[98:99], v[96:97] op_sel_hi:[0,1,1] neg_lo:[0,0,1] neg_hi:[0,0,1]
	v_pk_add_f32 v[12:13], v[98:99], v[12:13] neg_lo:[0,1] neg_hi:[0,1]
	v_lshlrev_b32_e32 v98, 16, v112
	v_and_b32_e32 v99, 0xffff0000, v112
	v_cvt_pk_bf16_f32 v100, v100, v101
	v_pk_add_f32 v[12:13], v[12:13], v[98:99]
	global_store_dword v[4:5], v100, off offset:2048
	v_cndmask_b32_e64 v100, v196, v195, s[54:55]
	v_and_b32_e32 v109, 0xffff0000, v113
	v_pk_add_f32 v[10:11], v[12:13], v[10:11] neg_lo:[0,1] neg_hi:[0,1]
	v_pk_fma_f32 v[100:101], v[100:101], v[12:13], v[98:99] op_sel_hi:[0,1,1] neg_lo:[0,0,1] neg_hi:[0,0,1]
	v_pk_add_f32 v[10:11], v[10:11], v[108:109]
	v_cvt_pk_bf16_f32 v107, v100, v101
	v_add_co_u32_e32 v100, vcc, s14, v4
	v_pk_fma_f32 v[12:13], v[10:11], s[56:57], v[108:109] op_sel_hi:[1,0,1] neg_lo:[0,0,1] neg_hi:[0,0,1]
	s_nop 0
	v_addc_co_u32_e32 v101, vcc, 0, v5, vcc
	v_cvt_pk_bf16_f32 v12, v12, v13
	global_store_dword v[100:101], v12, off offset:2048
	s_waitcnt vmcnt(14)
	v_lshlrev_b32_e32 v12, 16, v105
	v_and_b32_e32 v13, 0xffff0000, v105
	v_pk_add_f32 v[8:9], v[10:11], v[8:9] neg_lo:[0,1] neg_hi:[0,1]
	v_add_co_u32_e32 v102, vcc, s4, v4
	v_pk_add_f32 v[8:9], v[8:9], v[12:13]
	s_nop 0
	v_addc_co_u32_e32 v103, vcc, 0, v5, vcc
	v_pk_fma_f32 v[10:11], v[8:9], s[56:57], v[12:13] op_sel_hi:[1,0,1] neg_lo:[0,0,1] neg_hi:[0,0,1]
	v_pk_add_f32 v[8:9], v[8:9], v[96:97] neg_lo:[0,1] neg_hi:[0,1]
	v_cvt_pk_bf16_f32 v10, v10, v11
	global_store_dword v[102:103], v10, off
	s_waitcnt vmcnt(14)
; __device__ __forceinline__ f32x2 un2(unsigned u) { return (f32x2){bf_lo(u), bf_hi(u)}; }
; __device__ __forceinline__ void st2(bf16_t* p, f32x2 v) { *(unsigned*)p = cvt_pk_bf16(v.x, v.y); }
; template <int W>
; __device__ __forceinline__ void pool_branch(const bf16_t* __restrict__ Pb, bf16_t* __restrict__ out, bool first) {
;     ...
;     for (int i = 0; i < TT; ++i) {
;         const f32x2 ui = un2(raw[i + W - 1]);
;         S += ui;
;         const float inv = (first && (i + 1 < W)) ? 1.0f / (float)(i + 1) : 1.0f / (float)W;
;         st2(out + (size_t)i * EW, S * inv - ui);
;         S -= un2(raw[i]);
;     }
	v_lshlrev_b32_e32 v10, 16, v104
	v_and_b32_e32 v11, 0xffff0000, v104
	v_pk_add_f32 v[8:9], v[8:9], v[10:11]
	global_store_dword v[102:103], v107, off offset:-4096
	v_pk_fma_f32 v[96:97], v[8:9], s[56:57], v[10:11] op_sel_hi:[1,0,1] neg_lo:[0,0,1] neg_hi:[0,0,1]
	v_pk_add_f32 v[8:9], v[8:9], v[98:99] neg_lo:[0,1] neg_hi:[0,1]
	v_cvt_pk_bf16_f32 v96, v96, v97
	global_store_dword v[102:103], v96, off offset:2048
	s_waitcnt vmcnt(15)
	v_lshlrev_b32_e32 v96, 16, v114
	v_and_b32_e32 v97, 0xffff0000, v114
	v_pk_add_f32 v[8:9], v[8:9], v[96:97]
	s_movk_i32 s4, 0x4000
	v_pk_fma_f32 v[98:99], v[8:9], s[56:57], v[96:97] op_sel_hi:[1,0,1] neg_lo:[0,0,1] neg_hi:[0,0,1]
	s_waitcnt vmcnt(14)
	v_and_b32_e32 v103, 0xffff0000, v115
	v_cvt_pk_bf16_f32 v102, v98, v99
	v_add_co_u32_e32 v98, vcc, s12, v4
	v_pk_add_f32 v[8:9], v[8:9], v[108:109] neg_lo:[0,1] neg_hi:[0,1]
	s_nop 0
	v_addc_co_u32_e32 v99, vcc, 0, v5, vcc
	v_add_co_u32_e32 v100, vcc, s4, v4
	s_movk_i32 s4, 0x6000
	s_nop 0
	v_addc_co_u32_e32 v101, vcc, 0, v5, vcc
	global_store_dword v[100:101], v102, off offset:-4096
	v_lshlrev_b32_e32 v102, 16, v115
	v_pk_add_f32 v[8:9], v[8:9], v[102:103]
	s_nop 0
	v_pk_fma_f32 v[104:105], v[8:9], s[56:57], v[102:103] op_sel_hi:[1,0,1] neg_lo:[0,0,1] neg_hi:[0,0,1]
	v_pk_add_f32 v[8:9], v[8:9], v[12:13] neg_lo:[0,1] neg_hi:[0,1]
	v_cvt_pk_bf16_f32 v104, v104, v105
	global_store_dword v[98:99], v104, off offset:2048
	s_waitcnt vmcnt(15)
	v_lshlrev_b32_e32 v98, 16, v116
	v_and_b32_e32 v99, 0xffff0000, v116
	v_pk_add_f32 v[8:9], v[8:9], v[98:99]
	s_waitcnt vmcnt(12)
	v_and_b32_e32 v105, 0xffff0000, v119
	v_pk_fma_f32 v[12:13], v[8:9], s[56:57], v[98:99] op_sel_hi:[1,0,1] neg_lo:[0,0,1] neg_hi:[0,0,1]
	v_pk_add_f32 v[8:9], v[8:9], v[10:11] neg_lo:[0,1] neg_hi:[0,1]
	v_cvt_pk_bf16_f32 v12, v12, v13
	global_store_dword v[100:101], v12, off
	v_lshlrev_b32_e32 v12, 16, v117
	v_and_b32_e32 v13, 0xffff0000, v117
	v_pk_add_f32 v[8:9], v[8:9], v[12:13]
	s_nop 0
	v_pk_fma_f32 v[10:11], v[8:9], s[56:57], v[12:13] op_sel_hi:[1,0,1] neg_lo:[0,0,1] neg_hi:[0,0,1]
	v_pk_add_f32 v[8:9], v[8:9], v[96:97] neg_lo:[0,1] neg_hi:[0,1]
	v_cvt_pk_bf16_f32 v10, v10, v11
	global_store_dword v[100:101], v10, off offset:2048
	v_lshlrev_b32_e32 v10, 16, v118
	v_and_b32_e32 v11, 0xffff0000, v118
	v_pk_add_f32 v[8:9], v[8:9], v[10:11]
	s_nop 0
	v_pk_fma_f32 v[96:97], v[8:9], s[56:57], v[10:11] op_sel_hi:[1,0,1] neg_lo:[0,0,1] neg_hi:[0,0,1]
	v_pk_add_f32 v[8:9], v[8:9], v[102:103] neg_lo:[0,1] neg_hi:[0,1]
	v_cvt_pk_bf16_f32 v104, v96, v97
	v_add_co_u32_e32 v96, vcc, s5, v4
	s_nop 1
	v_addc_co_u32_e32 v97, vcc, 0, v5, vcc
	v_add_co_u32_e32 v100, vcc, s4, v4
	s_nop 1
	v_addc_co_u32_e32 v101, vcc, 0, v5, vcc
	global_store_dword v[100:101], v104, off offset:-4096
	v_lshlrev_b32_e32 v104, 16, v119
	v_pk_add_f32 v[8:9], v[8:9], v[104:105]
	s_nop 0
	v_pk_fma_f32 v[102:103], v[8:9], s[56:57], v[104:105] op_sel_hi:[1,0,1] neg_lo:[0,0,1] neg_hi:[0,0,1]
	v_pk_add_f32 v[8:9], v[8:9], v[98:99] neg_lo:[0,1] neg_hi:[0,1]
	v_cvt_pk_bf16_f32 v102, v102, v103
	global_store_dword v[96:97], v102, off offset:2048
	s_waitcnt vmcnt(15)
	v_lshlrev_b32_e32 v96, 16, v120
	v_and_b32_e32 v97, 0xffff0000, v120
	v_pk_add_f32 v[8:9], v[8:9], v[96:97]
	s_nop 0
	v_pk_fma_f32 v[96:97], v[8:9], s[56:57], v[96:97] op_sel_hi:[1,0,1] neg_lo:[0,0,1] neg_hi:[0,0,1]
	v_pk_add_f32 v[8:9], v[8:9], v[12:13] neg_lo:[0,1] neg_hi:[0,1]
	s_waitcnt vmcnt(14)
	v_lshlrev_b32_e32 v12, 16, v121
	v_and_b32_e32 v13, 0xffff0000, v121
	v_pk_add_f32 v[8:9], v[8:9], v[12:13]
	v_cvt_pk_bf16_f32 v96, v96, v97
	v_pk_fma_f32 v[12:13], v[8:9], s[56:57], v[12:13] op_sel_hi:[1,0,1] neg_lo:[0,0,1] neg_hi:[0,0,1]
	v_pk_add_f32 v[8:9], v[8:9], v[10:11] neg_lo:[0,1] neg_hi:[0,1]
	s_waitcnt vmcnt(13)
	v_lshlrev_b32_e32 v10, 16, v122
	v_and_b32_e32 v11, 0xffff0000, v122
	v_pk_add_f32 v[8:9], v[8:9], v[10:11]
	v_cvt_pk_bf16_f32 v12, v12, v13
	v_pk_fma_f32 v[10:11], v[8:9], s[56:57], v[10:11] op_sel_hi:[1,0,1] neg_lo:[0,0,1] neg_hi:[0,0,1]
	global_store_dword v[100:101], v12, off offset:2048
	v_cvt_pk_bf16_f32 v12, v10, v11
	v_add_co_u32_e32 v10, vcc, 0x7000, v4
	v_pk_add_f32 v[104:105], v[8:9], v[104:105] neg_lo:[0,1] neg_hi:[0,1]
	s_nop 0
	v_addc_co_u32_e32 v11, vcc, 0, v5, vcc
	global_store_dword v[100:101], v96, off
	global_store_dword v[10:11], v12, off
